# baseline (speedup 1.0000x reference)
; DEV float bf2f(u16 h) { return __uint_as_float(((uint32_t)h) << 16); }
; DEV float opq(float x) { asm volatile("" : "+v"(x)); return x; }
; DEV f32x4 mfma16(bf16x8 a, bf16x8 b, f32x4 c) { return __builtin_amdgcn_mfma_f32_16x16x32_bf16(a, b, c, 0, 0, 0); }
; DEV void pv_tile(const u16* sP, const u16* sVt, f32x4 (&o)[MT][8], int fr, int fq) {
; #pragma unroll
;   for (int ks = 0; ks < 2; ++ks) {
;     bf16x8 a[MT];
; #pragma unroll
;     for (int mt = 0; mt < MT; ++mt) a[mt] = *(const bf16x8*)(sP + (mt * 16 + fr) * VS + ks * 32 + fq * 8);
; #pragma unroll
;     for (int nt = 0; nt < 8; ++nt) {
;       bf16x8 b = *(const bf16x8*)(sVt + (nt * 16 + fr) * VS + ks * 32 + fq * 8);
; #pragma unroll
;       for (int mt = 0; mt < MT; ++mt) o[mt][nt] = mfma16(a[mt], b, o[mt][nt]);
;     }
;   }
; DEV void ret_out_item(const Params& p, int l, int item, unsigned char* smem) {
;     ...
; #pragma unroll
;   for (int mt = 0; mt < MT; ++mt)
; #pragma unroll
;     for (int j = 0; j < 4; ++j) {
;       float sm = 0.f;
; #pragma unroll
;       for (int nt = 0; nt < 8; ++nt) sm = opq(sm + opq(o[mt][nt][j]));
;       sm = grp16_sum(sm);
;       const float mu = opq(sm * (1.0f / 128.0f));
;       float vs = 0.f;
; #pragma unroll
;       for (int nt = 0; nt < 8; ++nt) { const float d = opq(opq(o[mt][nt][j]) - mu); vs = opq(vs + opq(d * d)); }
;       vs = grp16_sum(vs);
;       const float rstd = opq(rsqrtf(opq(vs * (1.0f / 128.0f) + 1e-5f)));
;       const size_t tok = tok0 + mt * 16 + fq * 4 + j;
;       const u16* __restrict__ gp = p.proj + tok * DIN + C_RG + h * 128;
;       u16* __restrict__ op = p.mix + tok * DM + h * 128;
;       float gv[8], wv[8];
; #pragma unroll
;       for (int nt = 0; nt < 8; ++nt) { gv[nt] = bf2f(gp[nt * 16 + fr]); wv[nt] = gw[nt * 16 + fr]; }
.LBB0_340:
	s_or_b64 exec, exec, s[0:1]
	ds_write_b16 v72, v0 offset:528
	s_waitcnt lgkmcnt(0)
	ds_read_b128 v[0:3], v69
	ds_read_b128 v[20:23], v67 offset:62464
	ds_read_b128 v[4:7], v67 offset:53248
	ds_read_b128 v[8:11], v67 offset:55552
	v_add_u32_e32 v24, 0xd000, v67
	ds_read_b128 v[12:15], v67 offset:57856
	ds_read_b128 v[16:19], v67 offset:60160
	v_lshlrev_b32_e32 v128, 1, v90
	s_waitcnt lgkmcnt(3)
	v_mfma_f32_16x16x32_bf16 v[4:7], v[0:3], v[4:7], v[32:35]
	s_lshl_b32 s0, s5, 2
	s_add_u32 s0, s16, s0
	s_addc_u32 s1, s17, 0
	v_mfma_f32_16x16x32_bf16 v[32:35], v[0:3], v[20:23], v[48:51]
	ds_read_b128 v[20:23], v67 offset:64768
	s_add_i32 s4, s4, s33
	s_cmpk_gt_i32 s4, 0x3ff
	s_waitcnt lgkmcnt(3)
	v_mfma_f32_16x16x32_bf16 v[8:11], v[0:3], v[8:11], v[36:39]
	v_add_u32_e32 v48, 0xd040, v67
	s_waitcnt lgkmcnt(0)
	v_mfma_f32_16x16x32_bf16 v[36:39], v[0:3], v[20:23], v[52:55]
	ds_read_b128 v[20:23], v24 offset:13824
	v_mfma_f32_16x16x32_bf16 v[12:15], v[0:3], v[12:15], v[40:43]
	s_waitcnt lgkmcnt(0)
	v_mfma_f32_16x16x32_bf16 v[40:43], v[0:3], v[20:23], v[56:59]
	ds_read_b128 v[20:23], v24 offset:16128
	v_mfma_f32_16x16x32_bf16 v[16:19], v[0:3], v[16:19], v[44:47]
	s_nop 2
	ds_read_b128 v[44:47], v69 offset:64
	s_waitcnt lgkmcnt(1)
	v_mfma_f32_16x16x32_bf16 v[0:3], v[0:3], v[20:23], v[60:63]
	ds_read_b128 v[20:23], v67 offset:53312
	s_waitcnt lgkmcnt(0)
	v_mfma_f32_16x16x32_bf16 v[28:31], v[44:47], v[20:23], v[4:7]
	s_nop 2
	ds_read_b128 v[4:7], v67 offset:55616
	s_waitcnt lgkmcnt(0)
	v_mfma_f32_16x16x32_bf16 v[24:27], v[44:47], v[4:7], v[8:11]
	ds_read_b128 v[4:7], v67 offset:57920
	s_waitcnt lgkmcnt(0)
	v_mfma_f32_16x16x32_bf16 v[20:23], v[44:47], v[4:7], v[12:15]
	ds_read_b128 v[4:7], v67 offset:60224
	s_waitcnt lgkmcnt(0)
	v_mfma_f32_16x16x32_bf16 v[16:19], v[44:47], v[4:7], v[16:19]
	ds_read_b128 v[4:7], v67 offset:62528
	s_waitcnt lgkmcnt(0)
	v_mfma_f32_16x16x32_bf16 v[12:15], v[44:47], v[4:7], v[32:35]
	ds_read_b128 v[4:7], v67 offset:64832
	s_nop 1
	ds_read_b128 v[32:35], v48 offset:16128
	s_waitcnt lgkmcnt(1)
	v_mfma_f32_16x16x32_bf16 v[8:11], v[44:47], v[4:7], v[36:39]
	ds_read_b128 v[4:7], v48 offset:13824
	s_nop 1
	v_mov_b64_e32 v[36:37], s[76:77]
	s_waitcnt lgkmcnt(1)
	v_mfma_f32_16x16x32_bf16 v[0:3], v[44:47], v[32:35], v[0:3]
	v_mov_b32_e32 v32, v28
	v_mov_b32_e32 v33, v24
	v_add_f32_e32 v32, 0, v32
	s_waitcnt lgkmcnt(0)
	v_mfma_f32_16x16x32_bf16 v[4:7], v[44:47], v[4:7], v[40:43]
	v_add_f32_e32 v32, v32, v33
	v_mov_b32_e32 v33, v20
	v_lshl_add_u64 v[34:35], s[6:7], 0, v[80:81]
	v_add_f32_e32 v32, v32, v33
	v_mov_b32_e32 v33, v16
	v_or_b32_e32 v34, v34, v83
	v_add_f32_e32 v32, v32, v33
	v_mov_b32_e32 v33, v12
	v_mul_lo_u32 v41, v35, s88
	v_add_f32_e32 v32, v32, v33
	v_mov_b32_e32 v33, v8
	s_nop 0
	v_add_f32_e32 v32, v32, v33
	v_mov_b32_e32 v33, v4
	s_nop 0
	v_add_f32_e32 v32, v32, v33
	v_mov_b32_e32 v33, v0
	s_nop 0
	v_add_f32_e32 v32, v32, v33
	v_mov_b32_e32 v33, v24
	s_nop 0
	v_add_f32_dpp v32, v32, v32 row_ror:8 row_mask:0xf bank_mask:0xf bound_ctrl:1
	s_nop 1
	v_add_f32_dpp v32, v32, v32 row_ror:4 row_mask:0xf bank_mask:0xf bound_ctrl:1
	s_nop 1
	v_add_f32_dpp v32, v32, v32 row_ror:2 row_mask:0xf bank_mask:0xf bound_ctrl:1
	s_nop 1
	v_add_f32_dpp v32, v32, v32 row_ror:1 row_mask:0xf bank_mask:0xf bound_ctrl:1
	s_nop 0
	v_mul_f32_e32 v42, 0x3c000000, v32
	v_mov_b32_e32 v32, v28
	s_nop 0
	v_sub_f32_e32 v32, v32, v42
	s_nop 0
	v_mul_f32_e32 v32, v32, v32
	s_nop 0
	v_add_f32_e32 v32, 0, v32
	s_nop 0
	v_sub_f32_e32 v33, v33, v42
	s_nop 0
	v_mul_f32_e32 v33, v33, v33
	s_nop 0
	v_add_f32_e32 v32, v32, v33
	v_mov_b32_e32 v33, v20
	s_nop 0
	v_sub_f32_e32 v33, v33, v42
	s_nop 0
	v_mul_f32_e32 v33, v33, v33
	s_nop 0
	v_add_f32_e32 v32, v32, v33
	v_mov_b32_e32 v33, v16
	s_nop 0
	v_sub_f32_e32 v33, v33, v42
	s_nop 0
	v_mul_f32_e32 v33, v33, v33
	s_nop 0
	v_add_f32_e32 v32, v32, v33
	v_mov_b32_e32 v33, v12
	s_nop 0
	v_sub_f32_e32 v33, v33, v42
	s_nop 0
	v_mul_f32_e32 v33, v33, v33
	s_nop 0
	v_add_f32_e32 v32, v32, v33
	v_mov_b32_e32 v33, v8
	s_nop 0
	v_sub_f32_e32 v33, v33, v42
	s_nop 0
	v_mul_f32_e32 v33, v33, v33
	s_nop 0
	v_add_f32_e32 v32, v32, v33
	v_mov_b32_e32 v33, v4
	s_nop 0
	v_sub_f32_e32 v33, v33, v42
	s_nop 0
	v_mul_f32_e32 v33, v33, v33
	s_nop 0
	v_add_f32_e32 v32, v32, v33
	v_mov_b32_e32 v33, v0
	s_nop 0
	v_sub_f32_e32 v33, v33, v42
	s_nop 0
	v_mul_f32_e32 v33, v33, v33
	s_nop 0
	v_add_f32_e32 v32, v32, v33
	s_nop 1
	v_add_f32_dpp v32, v32, v32 row_ror:8 row_mask:0xf bank_mask:0xf bound_ctrl:1
	s_nop 1
	v_add_f32_dpp v32, v32, v32 row_ror:4 row_mask:0xf bank_mask:0xf bound_ctrl:1
	s_nop 1
	v_add_f32_dpp v32, v32, v32 row_ror:2 row_mask:0xf bank_mask:0xf bound_ctrl:1
	s_nop 1
	v_add_f32_dpp v32, v32, v32 row_ror:1 row_mask:0xf bank_mask:0xf bound_ctrl:1
	s_nop 0
	v_fmamk_f32 v32, v32, 0x3c000000, v165
	s_nop 0
	v_cmp_gt_f32_e32 vcc, s84, v32
	v_mul_f32_e32 v33, 0x4b800000, v32
	s_nop 0
	v_cndmask_b32_e32 v32, v32, v33, vcc
	v_rsq_f32_e32 v32, v32
	s_nop 0
	v_mul_f32_e32 v33, 0x45800000, v32
	v_cndmask_b32_e32 v43, v32, v33, vcc
	v_mad_u64_u32 v[32:33], s[6:7], v34, s88, v[36:37]
	v_add_u32_e32 v33, v41, v33
	v_lshl_add_u64 v[38:39], v[32:33], 0, s[18:19]
	v_lshl_add_u64 v[38:39], v[38:39], 0, v[128:129]
	global_load_ushort v200, v[38:39], off offset:3072
	global_load_ushort v201, v[38:39], off offset:3104
	global_load_ushort v202, v[38:39], off offset:3136
	global_load_ushort v203, v[38:39], off offset:3168
	global_load_ushort v204, v[38:39], off offset:3200
	global_load_ushort v205, v[38:39], off offset:3232
	global_load_ushort v206, v[38:39], off offset:3264
	global_load_ushort v207, v[38:39], off offset:3296
	v_lshlrev_b32_e32 v216, 2, v90
	global_load_dword v208, v216, s[0:1]
	global_load_dword v209, v216, s[0:1] offset:64
	global_load_dword v210, v216, s[0:1] offset:128
	global_load_dword v211, v216, s[0:1] offset:192
	global_load_dword v212, v216, s[0:1] offset:256
	global_load_dword v213, v216, s[0:1] offset:320
	global_load_dword v214, v216, s[0:1] offset:384
	global_load_dword v215, v216, s[0:1] offset:448
	v_lshlrev_b64 v[32:33], 12, v[34:35]
	v_lshl_add_u64 v[48:49], s[78:79], 0, v[32:33]
	v_or_b32_e32 v34, 1, v34
	v_mad_u64_u32 v[36:37], s[6:7], v34, s88, v[36:37]
	v_add_u32_e32 v37, v41, v37
	v_lshl_add_u64 v[36:37], v[36:37], 0, s[18:19]
	v_lshlrev_b64 v[34:35], 12, v[34:35]
	s_waitcnt vmcnt(0)
; DEV float bf2f(u16 h) { return __uint_as_float(((uint32_t)h) << 16); }
; DEV float opq(float x) { asm volatile("" : "+v"(x)); return x; }
; DEV void ret_out_item(const Params& p, int l, int item, unsigned char* smem) {
;     ...
; #pragma unroll
;       for (int nt = 0; nt < 8; ++nt) { gv[nt] = bf2f(gp[nt * 16 + fr]); wv[nt] = gw[nt * 16 + fr]; }
; #pragma unroll
;       for (int nt = 0; nt < 8; ++nt) {
;         const float g = gv[nt];
;         const float silu = opq(__fdividef(g, 1.0f + __expf(-g)));
;         const float xn = opq(opq(opq(o[mt][nt][j]) - mu) * rstd);
;         op[nt * 16 + fr] = f2bf(opq(xn * wv[nt]) * silu);
;       }
	v_lshlrev_b32_e32 v50, 16, v200
	v_lshlrev_b32_e32 v40, 2, v90
	v_mov_b32_e32 v51, v208
	s_waitcnt vmcnt(0)
	v_lshlrev_b32_e32 v52, 16, v201
	v_mov_b32_e32 v53, v209
	s_waitcnt vmcnt(0)
	v_lshlrev_b32_e32 v54, 16, v202
	v_mov_b32_e32 v55, v210
	s_waitcnt vmcnt(0)
	v_lshlrev_b32_e32 v56, 16, v203
	v_mov_b32_e32 v57, v211
	s_waitcnt vmcnt(0)
	v_lshlrev_b32_e32 v58, 16, v204
	v_mov_b32_e32 v59, v212
	s_waitcnt vmcnt(0)
	v_lshlrev_b32_e32 v60, 16, v205
	v_mov_b32_e32 v61, v213
	v_mov_b32_e32 v46, v214
	s_nop 0
	s_waitcnt vmcnt(2)
	v_lshlrev_b32_e32 v47, 16, v206
	s_waitcnt vmcnt(0)
	v_lshlrev_b32_e32 v45, 16, v207
	v_lshl_add_u64 v[38:39], v[48:49], 0, s[18:19]
	v_mul_f32_e32 v48, 0xbfb8aa3b, v50
	v_exp_f32_e32 v48, v48
	v_mov_b32_e32 v44, v215
	v_lshl_add_u64 v[38:39], v[38:39], 0, v[128:129]
	v_add_f32_e32 v48, 1.0, v48
	v_div_scale_f32 v49, s[6:7], v48, v48, v50
	v_rcp_f32_e32 v62, v49
	s_nop 0
	v_fma_f32 v63, -v49, v62, 1.0
	v_fmac_f32_e32 v62, v63, v62
	v_div_scale_f32 v63, vcc, v50, v48, v50
	v_mul_f32_e32 v64, v63, v62
	v_fma_f32 v65, -v49, v64, v63
	v_fmac_f32_e32 v64, v65, v62
	v_fma_f32 v49, -v49, v64, v63
	v_div_fmas_f32 v49, v49, v62, v64
	v_div_fixup_f32 v48, v49, v48, v50
	s_nop 0
	v_sub_f32_e32 v28, v28, v42
	s_nop 0
	v_mul_f32_e32 v28, v43, v28
	s_nop 0
	v_mul_f32_e32 v28, v51, v28
	s_nop 0
	v_mul_f32_e32 v28, v48, v28
	v_cvt_pk_bf16_f32 v28, v28, s0
	global_store_short v[38:39], v28, off
	v_mul_f32_e32 v28, 0xbfb8aa3b, v52
	v_exp_f32_e32 v28, v28
	s_nop 0
	v_add_f32_e32 v28, 1.0, v28
	v_div_scale_f32 v48, s[6:7], v28, v28, v52
	v_rcp_f32_e32 v49, v48
	s_nop 0
	v_fma_f32 v50, -v48, v49, 1.0
	v_fmac_f32_e32 v49, v50, v49
	v_div_scale_f32 v50, vcc, v52, v28, v52
	v_mul_f32_e32 v51, v50, v49
	v_fma_f32 v62, -v48, v51, v50
	v_fmac_f32_e32 v51, v62, v49
	v_fma_f32 v48, -v48, v51, v50
	v_div_fmas_f32 v48, v48, v49, v51
	v_div_fixup_f32 v28, v48, v28, v52
	s_nop 0
	v_sub_f32_e32 v24, v24, v42
	s_nop 0
	v_mul_f32_e32 v24, v43, v24
	s_nop 0
	v_mul_f32_e32 v24, v53, v24
	s_nop 0
	v_mul_f32_e32 v24, v28, v24
	v_cvt_pk_bf16_f32 v24, v24, s0
	global_store_short v[38:39], v24, off offset:32
	v_mul_f32_e32 v24, 0xbfb8aa3b, v54
	v_exp_f32_e32 v24, v24
	s_nop 0
	v_add_f32_e32 v24, 1.0, v24
	v_div_scale_f32 v28, s[6:7], v24, v24, v54
	v_rcp_f32_e32 v48, v28
	s_nop 0
	v_fma_f32 v49, -v28, v48, 1.0
	v_fmac_f32_e32 v48, v49, v48
	v_div_scale_f32 v49, vcc, v54, v24, v54
	v_mul_f32_e32 v50, v49, v48
	v_fma_f32 v51, -v28, v50, v49
	v_fmac_f32_e32 v50, v51, v48
	v_fma_f32 v28, -v28, v50, v49
	v_div_fmas_f32 v28, v28, v48, v50
	v_div_fixup_f32 v24, v28, v24, v54
	s_nop 0
	v_sub_f32_e32 v20, v20, v42
	s_nop 0
	v_mul_f32_e32 v20, v43, v20
	s_nop 0
	v_mul_f32_e32 v20, v55, v20
	s_nop 0
	v_mul_f32_e32 v20, v24, v20
	v_cvt_pk_bf16_f32 v20, v20, s0
	global_store_short v[38:39], v20, off offset:64
	v_mul_f32_e32 v20, 0xbfb8aa3b, v56
	v_exp_f32_e32 v20, v20
	s_nop 0
	v_add_f32_e32 v20, 1.0, v20
	v_div_scale_f32 v24, s[6:7], v20, v20, v56
	v_rcp_f32_e32 v28, v24
	s_nop 0
	v_fma_f32 v48, -v24, v28, 1.0
	v_fmac_f32_e32 v28, v48, v28
	v_div_scale_f32 v48, vcc, v56, v20, v56
	v_mul_f32_e32 v49, v48, v28
	v_fma_f32 v50, -v24, v49, v48
	v_fmac_f32_e32 v49, v50, v28
	v_fma_f32 v24, -v24, v49, v48
	v_div_fmas_f32 v24, v24, v28, v49
	v_div_fixup_f32 v20, v24, v20, v56
	s_nop 0
	v_sub_f32_e32 v16, v16, v42
	s_nop 0
	v_mul_f32_e32 v16, v43, v16
	s_nop 0
	v_mul_f32_e32 v16, v57, v16
	s_nop 0
	v_mul_f32_e32 v16, v20, v16
	v_cvt_pk_bf16_f32 v16, v16, s0
	global_store_short v[38:39], v16, off offset:96
	v_mul_f32_e32 v16, 0xbfb8aa3b, v58
	v_exp_f32_e32 v16, v16
	s_nop 0
	v_add_f32_e32 v16, 1.0, v16
	v_div_scale_f32 v20, s[6:7], v16, v16, v58
	v_rcp_f32_e32 v24, v20
	s_nop 0
	v_fma_f32 v28, -v20, v24, 1.0
	v_fmac_f32_e32 v24, v28, v24
	v_div_scale_f32 v28, vcc, v58, v16, v58
	v_mul_f32_e32 v48, v28, v24
	v_fma_f32 v49, -v20, v48, v28
	v_fmac_f32_e32 v48, v49, v24
	v_fma_f32 v20, -v20, v48, v28
	v_div_fmas_f32 v20, v20, v24, v48
	v_div_fixup_f32 v16, v20, v16, v58
	s_nop 0
	v_sub_f32_e32 v12, v12, v42
	s_nop 0
	v_mul_f32_e32 v12, v43, v12
	s_nop 0
	v_mul_f32_e32 v12, v59, v12
	s_nop 0
	v_mul_f32_e32 v12, v16, v12
	v_cvt_pk_bf16_f32 v12, v12, s0
	global_store_short v[38:39], v12, off offset:128
	v_mul_f32_e32 v12, 0xbfb8aa3b, v60
	v_exp_f32_e32 v12, v12
	s_nop 0
	v_add_f32_e32 v12, 1.0, v12
	v_div_scale_f32 v16, s[6:7], v12, v12, v60
	v_rcp_f32_e32 v20, v16
	s_nop 0
	v_fma_f32 v24, -v16, v20, 1.0
	v_fmac_f32_e32 v20, v24, v20
	v_div_scale_f32 v24, vcc, v60, v12, v60
	v_mul_f32_e32 v28, v24, v20
	v_fma_f32 v48, -v16, v28, v24
	v_fmac_f32_e32 v28, v48, v20
	v_fma_f32 v16, -v16, v28, v24
	v_div_fmas_f32 v16, v16, v20, v28
	v_div_fixup_f32 v12, v16, v12, v60
	s_nop 0
	v_sub_f32_e32 v8, v8, v42
	s_nop 0
	v_mul_f32_e32 v8, v43, v8
	s_nop 0
	v_mul_f32_e32 v8, v61, v8
	s_nop 0
	v_mul_f32_e32 v8, v12, v8
	v_cvt_pk_bf16_f32 v8, v8, s0
	global_store_short v[38:39], v8, off offset:160
	v_mul_f32_e32 v8, 0xbfb8aa3b, v47
	v_exp_f32_e32 v8, v8
	s_nop 0
	v_add_f32_e32 v8, 1.0, v8
	v_div_scale_f32 v12, s[6:7], v8, v8, v47
	v_rcp_f32_e32 v16, v12
	s_nop 0
	v_fma_f32 v20, -v12, v16, 1.0
	v_fmac_f32_e32 v16, v20, v16
	v_div_scale_f32 v20, vcc, v47, v8, v47
	v_mul_f32_e32 v24, v20, v16
	v_fma_f32 v28, -v12, v24, v20
	v_fmac_f32_e32 v24, v28, v16
	v_fma_f32 v12, -v12, v24, v20
	v_div_fmas_f32 v12, v12, v16, v24
	v_div_fixup_f32 v8, v12, v8, v47
	s_nop 0
	v_sub_f32_e32 v4, v4, v42
	s_nop 0
	v_mul_f32_e32 v4, v43, v4
	s_nop 0
	v_mul_f32_e32 v4, v46, v4
	s_nop 0
	v_mul_f32_e32 v4, v8, v4
	v_cvt_pk_bf16_f32 v4, v4, s0
	global_store_short v[38:39], v4, off offset:192
	v_mul_f32_e32 v4, 0xbfb8aa3b, v45
	v_exp_f32_e32 v4, v4
	s_nop 0
	v_add_f32_e32 v4, 1.0, v4
	v_div_scale_f32 v8, s[6:7], v4, v4, v45
	v_rcp_f32_e32 v12, v8
	s_nop 0
	v_fma_f32 v16, -v8, v12, 1.0
	v_fmac_f32_e32 v12, v16, v12
	v_div_scale_f32 v16, vcc, v45, v4, v45
	v_mul_f32_e32 v20, v16, v12
	v_fma_f32 v24, -v8, v20, v16
	v_fmac_f32_e32 v20, v24, v12
	v_fma_f32 v8, -v8, v20, v16
	v_div_fmas_f32 v8, v8, v12, v20
	v_div_fixup_f32 v4, v8, v4, v45
	v_mov_b32_e32 v8, v25
	v_sub_f32_e32 v0, v0, v42
	s_nop 0
	v_mul_f32_e32 v0, v43, v0
	s_waitcnt vmcnt(7)
; DEV float bf2f(u16 h) { return __uint_as_float(((uint32_t)h) << 16); }
; DEV float opq(float x) { asm volatile("" : "+v"(x)); return x; }
; DEV void ret_out_item(const Params& p, int l, int item, unsigned char* smem) {
;     ...
;       float sm = 0.f;
; #pragma unroll
;       for (int nt = 0; nt < 8; ++nt) sm = opq(sm + opq(o[mt][nt][j]));
;       sm = grp16_sum(sm);
;       const float mu = opq(sm * (1.0f / 128.0f));
;       float vs = 0.f;
; #pragma unroll
;       for (int nt = 0; nt < 8; ++nt) { const float d = opq(opq(o[mt][nt][j]) - mu); vs = opq(vs + opq(d * d)); }
;       vs = grp16_sum(vs);
;       const float rstd = opq(rsqrtf(opq(vs * (1.0f / 128.0f) + 1e-5f)));
;       const size_t tok = tok0 + mt * 16 + fq * 4 + j;
;       const u16* __restrict__ gp = p.proj + tok * DIN + C_RG + h * 128;
;       u16* __restrict__ op = p.mix + tok * DM + h * 128;
;       float gv[8], wv[8];
; #pragma unroll
;       for (int nt = 0; nt < 8; ++nt) { gv[nt] = bf2f(gp[nt * 16 + fr]); wv[nt] = gw[nt * 16 + fr]; }
; #pragma unroll
;       for (int nt = 0; nt < 8; ++nt) {
;         const float g = gv[nt];
;         const float silu = opq(__fdividef(g, 1.0f + __expf(-g)));
;         const float xn = opq(opq(opq(o[mt][nt][j]) - mu) * rstd);
;         op[nt * 16 + fr] = f2bf(opq(xn * wv[nt]) * silu);
	v_mul_f32_e32 v0, v44, v0
	s_nop 0
	v_mul_f32_e32 v0, v4, v0
	v_cvt_pk_bf16_f32 v0, v0, s0
	global_store_short v[38:39], v0, off offset:224
	v_mov_b32_e32 v0, v29
	v_mov_b32_e32 v4, v25
	v_add_f32_e32 v0, 0, v0
	v_lshl_add_u64 v[38:39], s[78:79], 0, v[34:35]
	v_add_f32_e32 v0, v0, v4
	v_mov_b32_e32 v4, v21
	v_lshl_add_u64 v[34:35], v[36:37], 0, v[128:129]
	v_add_f32_e32 v0, v0, v4
	v_mov_b32_e32 v4, v17
	v_lshl_add_u64 v[36:37], v[38:39], 0, s[18:19]
	v_add_f32_e32 v0, v0, v4
	v_mov_b32_e32 v4, v13
	s_nop 0
	v_add_f32_e32 v0, v0, v4
	v_mov_b32_e32 v4, v9
	s_nop 0
	v_add_f32_e32 v0, v0, v4
	v_mov_b32_e32 v4, v5
	s_nop 0
	v_add_f32_e32 v0, v0, v4
	v_mov_b32_e32 v4, v1
	s_nop 0
	v_add_f32_e32 v0, v0, v4
	v_mov_b32_e32 v4, v29
	s_nop 0
	v_add_f32_dpp v0, v0, v0 row_ror:8 row_mask:0xf bank_mask:0xf bound_ctrl:1
	s_nop 1
	v_add_f32_dpp v0, v0, v0 row_ror:4 row_mask:0xf bank_mask:0xf bound_ctrl:1
	s_nop 1
	v_add_f32_dpp v0, v0, v0 row_ror:2 row_mask:0xf bank_mask:0xf bound_ctrl:1
	s_nop 1
	v_add_f32_dpp v0, v0, v0 row_ror:1 row_mask:0xf bank_mask:0xf bound_ctrl:1
	s_nop 0
	v_mul_f32_e32 v0, 0x3c000000, v0
	s_nop 0
	v_sub_f32_e32 v4, v4, v0
	s_nop 0
	v_mul_f32_e32 v4, v4, v4
	s_nop 0
	v_add_f32_e32 v4, 0, v4
	s_nop 0
	v_sub_f32_e32 v8, v8, v0
	s_nop 0
	v_mul_f32_e32 v8, v8, v8
	s_nop 0
	v_add_f32_e32 v4, v4, v8
	v_mov_b32_e32 v8, v21
	s_nop 0
	v_sub_f32_e32 v8, v8, v0
	s_nop 0
	v_mul_f32_e32 v8, v8, v8
	s_nop 0
	v_add_f32_e32 v4, v4, v8
	v_mov_b32_e32 v8, v17
	s_nop 0
	v_sub_f32_e32 v8, v8, v0
	s_nop 0
	v_mul_f32_e32 v8, v8, v8
	s_nop 0
	v_add_f32_e32 v4, v4, v8
	v_mov_b32_e32 v8, v13
	s_nop 0
	v_sub_f32_e32 v8, v8, v0
	s_nop 0
	v_mul_f32_e32 v8, v8, v8
	s_nop 0
	v_add_f32_e32 v4, v4, v8
	v_mov_b32_e32 v8, v9
	s_nop 0
	v_sub_f32_e32 v8, v8, v0
	s_nop 0
	v_mul_f32_e32 v8, v8, v8
	s_nop 0
	v_add_f32_e32 v4, v4, v8
	v_mov_b32_e32 v8, v5
	s_nop 0
	v_sub_f32_e32 v8, v8, v0
	s_nop 0
	v_mul_f32_e32 v8, v8, v8
	s_nop 0
	v_add_f32_e32 v4, v4, v8
	v_mov_b32_e32 v8, v1
	s_nop 0
	v_sub_f32_e32 v8, v8, v0
	s_nop 0
	v_mul_f32_e32 v8, v8, v8
	s_nop 0
	v_add_f32_e32 v4, v4, v8
	s_nop 1
	v_add_f32_dpp v4, v4, v4 row_ror:8 row_mask:0xf bank_mask:0xf bound_ctrl:1
	s_nop 1
	v_add_f32_dpp v4, v4, v4 row_ror:4 row_mask:0xf bank_mask:0xf bound_ctrl:1
	s_nop 1
	v_add_f32_dpp v4, v4, v4 row_ror:2 row_mask:0xf bank_mask:0xf bound_ctrl:1
	s_nop 1
	v_add_f32_dpp v4, v4, v4 row_ror:1 row_mask:0xf bank_mask:0xf bound_ctrl:1
	s_nop 0
	v_fmamk_f32 v4, v4, 0x3c000000, v165
	s_nop 0
	v_cmp_gt_f32_e32 vcc, s84, v4
	v_mul_f32_e32 v8, 0x4b800000, v4
	s_nop 0
	v_cndmask_b32_e32 v4, v4, v8, vcc
	v_rsq_f32_e32 v4, v4
	s_nop 0
	v_mul_f32_e32 v8, 0x45800000, v4
	v_cndmask_b32_e32 v4, v4, v8, vcc
	global_load_ushort v200, v[34:35], off offset:3072
	global_load_ushort v201, v[34:35], off offset:3104
	global_load_ushort v202, v[34:35], off offset:3136
	global_load_ushort v203, v[34:35], off offset:3168
	global_load_ushort v204, v[34:35], off offset:3200
	global_load_ushort v205, v[34:35], off offset:3232
	global_load_ushort v206, v[34:35], off offset:3264
	global_load_ushort v207, v[34:35], off offset:3296
	v_lshlrev_b32_e32 v216, 2, v90
	global_load_dword v208, v216, s[0:1]
	global_load_dword v209, v216, s[0:1] offset:64
	global_load_dword v210, v216, s[0:1] offset:128
	global_load_dword v211, v216, s[0:1] offset:192
	global_load_dword v212, v216, s[0:1] offset:256
	global_load_dword v213, v216, s[0:1] offset:320
	global_load_dword v214, v216, s[0:1] offset:384
	global_load_dword v215, v216, s[0:1] offset:448
	s_waitcnt vmcnt(0)
	v_lshlrev_b32_e32 v24, 16, v200
	v_mov_b32_e32 v28, v208
	v_mul_f32_e32 v38, 0xbfb8aa3b, v24
	v_exp_f32_e32 v38, v38
	s_waitcnt vmcnt(0)
	v_lshlrev_b32_e32 v41, 16, v201
	v_mov_b32_e32 v42, v209
	v_add_f32_e32 v38, 1.0, v38
	v_div_scale_f32 v39, s[6:7], v38, v38, v24
	v_rcp_f32_e32 v51, v39
	s_waitcnt vmcnt(0)
	v_lshlrev_b32_e32 v43, 16, v202
	v_mov_b32_e32 v44, v210
	v_fma_f32 v52, -v39, v51, 1.0
	v_fmac_f32_e32 v51, v52, v51
	v_div_scale_f32 v52, vcc, v24, v38, v24
	v_mul_f32_e32 v53, v52, v51
	v_fma_f32 v54, -v39, v53, v52
	v_fmac_f32_e32 v53, v54, v51
	v_fma_f32 v39, -v39, v53, v52
	v_div_fmas_f32 v39, v39, v51, v53
	v_div_fixup_f32 v24, v39, v38, v24
	s_waitcnt vmcnt(0)
	v_lshlrev_b32_e32 v45, 16, v203
	v_mov_b32_e32 v46, v211
	s_waitcnt vmcnt(0)
	v_lshlrev_b32_e32 v47, 16, v204
	v_mov_b32_e32 v48, v212
	s_waitcnt vmcnt(0)
	v_lshlrev_b32_e32 v49, 16, v205
	v_mov_b32_e32 v50, v213
	s_waitcnt vmcnt(0)
	v_lshlrev_b32_e32 v20, 16, v206
	v_mov_b32_e32 v16, v214
	s_waitcnt vmcnt(0)
; DEV float opq(float x) { asm volatile("" : "+v"(x)); return x; }
; DEV void ret_out_item(const Params& p, int l, int item, unsigned char* smem) {
;     ...
; #pragma unroll
;       for (int nt = 0; nt < 8; ++nt) {
;         const float g = gv[nt];
;         const float silu = opq(__fdividef(g, 1.0f + __expf(-g)));
;         const float xn = opq(opq(opq(o[mt][nt][j]) - mu) * rstd);
;         op[nt * 16 + fr] = f2bf(opq(xn * wv[nt]) * silu);
;       }
	v_lshlrev_b32_e32 v12, 16, v207
	v_mov_b32_e32 v8, v215
	s_nop 0
	v_sub_f32_e32 v29, v29, v0
	s_nop 0
	v_mul_f32_e32 v29, v4, v29
	s_nop 0
	v_mul_f32_e32 v28, v28, v29
	s_nop 0
	v_mul_f32_e32 v24, v24, v28
	v_cvt_pk_bf16_f32 v24, v24, s0
	v_lshl_add_u64 v[28:29], v[36:37], 0, v[128:129]
	global_store_short v[28:29], v24, off
	v_mul_f32_e32 v24, 0xbfb8aa3b, v41
	v_exp_f32_e32 v24, v24
	s_nop 0
	v_add_f32_e32 v24, 1.0, v24
	v_div_scale_f32 v36, s[6:7], v24, v24, v41
	v_rcp_f32_e32 v37, v36
	s_nop 0
	v_fma_f32 v38, -v36, v37, 1.0
	v_fmac_f32_e32 v37, v38, v37
	v_div_scale_f32 v38, vcc, v41, v24, v41
	v_mul_f32_e32 v39, v38, v37
	v_fma_f32 v51, -v36, v39, v38
	v_fmac_f32_e32 v39, v51, v37
	v_fma_f32 v36, -v36, v39, v38
	v_div_fmas_f32 v36, v36, v37, v39
	v_div_fixup_f32 v24, v36, v24, v41
	s_nop 0
	v_sub_f32_e32 v25, v25, v0
	s_nop 0
	v_mul_f32_e32 v25, v4, v25
	s_nop 0
	v_mul_f32_e32 v25, v42, v25
	s_nop 0
	v_mul_f32_e32 v24, v24, v25
	v_cvt_pk_bf16_f32 v24, v24, s0
	global_store_short v[28:29], v24, off offset:32
	v_mul_f32_e32 v24, 0xbfb8aa3b, v43
	v_exp_f32_e32 v24, v24
	s_nop 0
	v_add_f32_e32 v24, 1.0, v24
	v_div_scale_f32 v25, s[6:7], v24, v24, v43
	v_rcp_f32_e32 v36, v25
	s_nop 0
	v_fma_f32 v37, -v25, v36, 1.0
	v_fmac_f32_e32 v36, v37, v36
	v_div_scale_f32 v37, vcc, v43, v24, v43
	v_mul_f32_e32 v38, v37, v36
	v_fma_f32 v39, -v25, v38, v37
	v_fmac_f32_e32 v38, v39, v36
	v_fma_f32 v25, -v25, v38, v37
	v_div_fmas_f32 v25, v25, v36, v38
	v_div_fixup_f32 v24, v25, v24, v43
	s_nop 0
	v_sub_f32_e32 v21, v21, v0
	s_nop 0
	v_mul_f32_e32 v21, v4, v21
	s_nop 0
	v_mul_f32_e32 v21, v44, v21
	s_nop 0
	v_mul_f32_e32 v21, v24, v21
	v_cvt_pk_bf16_f32 v21, v21, s0
	global_store_short v[28:29], v21, off offset:64
	v_mul_f32_e32 v21, 0xbfb8aa3b, v45
	v_exp_f32_e32 v21, v21
	s_nop 0
	v_add_f32_e32 v21, 1.0, v21
	v_div_scale_f32 v24, s[6:7], v21, v21, v45
	v_rcp_f32_e32 v25, v24
	s_nop 0
	v_fma_f32 v36, -v24, v25, 1.0
	v_fmac_f32_e32 v25, v36, v25
	v_div_scale_f32 v36, vcc, v45, v21, v45
	v_mul_f32_e32 v37, v36, v25
	v_fma_f32 v38, -v24, v37, v36
	v_fmac_f32_e32 v37, v38, v25
	v_fma_f32 v24, -v24, v37, v36
	v_div_fmas_f32 v24, v24, v25, v37
	v_div_fixup_f32 v21, v24, v21, v45
	s_nop 0
	v_sub_f32_e32 v17, v17, v0
	s_nop 0
	v_mul_f32_e32 v17, v4, v17
	s_nop 0
	v_mul_f32_e32 v17, v46, v17
	s_nop 0
	v_mul_f32_e32 v17, v21, v17
	v_cvt_pk_bf16_f32 v17, v17, s0
	global_store_short v[28:29], v17, off offset:96
	v_mul_f32_e32 v17, 0xbfb8aa3b, v47
	v_exp_f32_e32 v17, v17
	s_nop 0
	v_add_f32_e32 v17, 1.0, v17
	v_div_scale_f32 v21, s[6:7], v17, v17, v47
	v_rcp_f32_e32 v24, v21
	s_nop 0
	v_fma_f32 v25, -v21, v24, 1.0
	v_fmac_f32_e32 v24, v25, v24
	v_div_scale_f32 v25, vcc, v47, v17, v47
	v_mul_f32_e32 v36, v25, v24
	v_fma_f32 v37, -v21, v36, v25
	v_fmac_f32_e32 v36, v37, v24
	v_fma_f32 v21, -v21, v36, v25
	v_div_fmas_f32 v21, v21, v24, v36
	v_div_fixup_f32 v17, v21, v17, v47
	s_nop 0
	v_sub_f32_e32 v13, v13, v0
	s_nop 0
	v_mul_f32_e32 v13, v4, v13
	s_nop 0
	v_mul_f32_e32 v13, v48, v13
	s_nop 0
	v_mul_f32_e32 v13, v17, v13
	v_cvt_pk_bf16_f32 v13, v13, s0
	global_store_short v[28:29], v13, off offset:128
	v_mul_f32_e32 v13, 0xbfb8aa3b, v49
	v_exp_f32_e32 v13, v13
	s_nop 0
	v_add_f32_e32 v13, 1.0, v13
	v_div_scale_f32 v17, s[6:7], v13, v13, v49
	v_rcp_f32_e32 v21, v17
	s_nop 0
	v_fma_f32 v24, -v17, v21, 1.0
	v_fmac_f32_e32 v21, v24, v21
	v_div_scale_f32 v24, vcc, v49, v13, v49
	v_mul_f32_e32 v25, v24, v21
	v_fma_f32 v36, -v17, v25, v24
	v_fmac_f32_e32 v25, v36, v21
	v_fma_f32 v17, -v17, v25, v24
	v_div_fmas_f32 v17, v17, v21, v25
	v_div_fixup_f32 v13, v17, v13, v49
	s_nop 0
	v_sub_f32_e32 v9, v9, v0
	s_nop 0
	v_mul_f32_e32 v9, v4, v9
	s_nop 0
	v_mul_f32_e32 v9, v50, v9
	s_nop 0
	v_mul_f32_e32 v9, v13, v9
	v_cvt_pk_bf16_f32 v9, v9, s0
	global_store_short v[28:29], v9, off offset:160
	v_mul_f32_e32 v9, 0xbfb8aa3b, v20
	v_exp_f32_e32 v9, v9
	s_nop 0
	v_add_f32_e32 v9, 1.0, v9
	v_div_scale_f32 v13, s[6:7], v9, v9, v20
	v_rcp_f32_e32 v17, v13
	s_nop 0
	v_fma_f32 v21, -v13, v17, 1.0
	v_fmac_f32_e32 v17, v21, v17
	v_div_scale_f32 v21, vcc, v20, v9, v20
	v_mul_f32_e32 v24, v21, v17
	v_fma_f32 v25, -v13, v24, v21
	v_fmac_f32_e32 v24, v25, v17
	v_fma_f32 v13, -v13, v24, v21
	v_div_fmas_f32 v13, v13, v17, v24
	v_div_fixup_f32 v9, v13, v9, v20
	s_nop 0
	v_sub_f32_e32 v5, v5, v0
	s_nop 0
	v_mul_f32_e32 v5, v4, v5
	s_nop 0
	v_mul_f32_e32 v5, v16, v5
	s_nop 0
	v_mul_f32_e32 v5, v9, v5
	v_cvt_pk_bf16_f32 v5, v5, s0
	global_store_short v[28:29], v5, off offset:192
	v_mul_f32_e32 v5, 0xbfb8aa3b, v12
	v_exp_f32_e32 v5, v5
	s_nop 0
	v_add_f32_e32 v5, 1.0, v5
	v_div_scale_f32 v9, s[6:7], v5, v5, v12
	v_rcp_f32_e32 v13, v9
	s_mov_b64 s[6:7], 0x2800
	v_fma_f32 v16, -v9, v13, 1.0
	v_fmac_f32_e32 v13, v16, v13
	v_div_scale_f32 v16, vcc, v12, v5, v12
	v_mul_f32_e32 v17, v16, v13
	v_fma_f32 v20, -v9, v17, v16
	v_fmac_f32_e32 v17, v20, v13
	v_fma_f32 v9, -v9, v17, v16
	v_div_fmas_f32 v9, v9, v13, v17
	v_div_fixup_f32 v5, v9, v5, v12
	s_nop 0
	v_sub_f32_e32 v0, v1, v0
	v_mov_b32_e32 v1, v26
	v_mul_f32_e32 v0, v4, v0
	s_waitcnt vmcnt(7)
; DEV float bf2f(u16 h) { return __uint_as_float(((uint32_t)h) << 16); }
; DEV float opq(float x) { asm volatile("" : "+v"(x)); return x; }
; DEV void ret_out_item(const Params& p, int l, int item, unsigned char* smem) {
;     ...
;       float sm = 0.f;
; #pragma unroll
;       for (int nt = 0; nt < 8; ++nt) sm = opq(sm + opq(o[mt][nt][j]));
;       sm = grp16_sum(sm);
;       const float mu = opq(sm * (1.0f / 128.0f));
;       float vs = 0.f;
; #pragma unroll
;       for (int nt = 0; nt < 8; ++nt) { const float d = opq(opq(o[mt][nt][j]) - mu); vs = opq(vs + opq(d * d)); }
;       vs = grp16_sum(vs);
;       const float rstd = opq(rsqrtf(opq(vs * (1.0f / 128.0f) + 1e-5f)));
;       const size_t tok = tok0 + mt * 16 + fq * 4 + j;
;       const u16* __restrict__ gp = p.proj + tok * DIN + C_RG + h * 128;
;       u16* __restrict__ op = p.mix + tok * DM + h * 128;
;       float gv[8], wv[8];
; #pragma unroll
;       for (int nt = 0; nt < 8; ++nt) { gv[nt] = bf2f(gp[nt * 16 + fr]); wv[nt] = gw[nt * 16 + fr]; }
	v_mul_f32_e32 v0, v8, v0
	v_lshl_add_u64 v[8:9], v[34:35], 0, s[6:7]
	v_mul_f32_e32 v0, v5, v0
	v_cvt_pk_bf16_f32 v0, v0, s0
	global_store_short v[28:29], v0, off offset:224
	v_mov_b32_e32 v0, v30
	s_nop 0
	v_add_f32_e32 v0, 0, v0
	s_nop 0
	v_add_f32_e32 v0, v0, v1
	v_mov_b32_e32 v1, v22
	s_nop 0
	v_add_f32_e32 v0, v0, v1
	v_mov_b32_e32 v1, v18
	s_nop 0
	v_add_f32_e32 v0, v0, v1
	v_mov_b32_e32 v1, v14
	s_nop 0
	v_add_f32_e32 v0, v0, v1
	v_mov_b32_e32 v1, v10
	s_nop 0
	v_add_f32_e32 v0, v0, v1
	v_mov_b32_e32 v1, v6
	s_nop 0
	v_add_f32_e32 v0, v0, v1
	v_mov_b32_e32 v1, v2
	s_nop 0
	v_add_f32_e32 v0, v0, v1
	v_mov_b32_e32 v1, v26
	s_nop 0
	v_add_f32_dpp v0, v0, v0 row_ror:8 row_mask:0xf bank_mask:0xf bound_ctrl:1
	s_nop 1
	v_add_f32_dpp v0, v0, v0 row_ror:4 row_mask:0xf bank_mask:0xf bound_ctrl:1
	s_nop 1
	v_add_f32_dpp v0, v0, v0 row_ror:2 row_mask:0xf bank_mask:0xf bound_ctrl:1
	s_nop 1
	v_add_f32_dpp v0, v0, v0 row_ror:1 row_mask:0xf bank_mask:0xf bound_ctrl:1
	s_nop 0
	v_mul_f32_e32 v4, 0x3c000000, v0
	v_mov_b32_e32 v0, v30
	s_nop 0
	v_sub_f32_e32 v0, v0, v4
	s_nop 0
	v_mul_f32_e32 v0, v0, v0
	s_nop 0
	v_add_f32_e32 v0, 0, v0
	s_nop 0
	v_sub_f32_e32 v1, v1, v4
	s_nop 0
	v_mul_f32_e32 v1, v1, v1
	s_nop 0
	v_add_f32_e32 v0, v0, v1
	v_mov_b32_e32 v1, v22
	s_nop 0
	v_sub_f32_e32 v1, v1, v4
	s_nop 0
	v_mul_f32_e32 v1, v1, v1
	s_nop 0
	v_add_f32_e32 v0, v0, v1
	v_mov_b32_e32 v1, v18
	s_nop 0
	v_sub_f32_e32 v1, v1, v4
	s_nop 0
	v_mul_f32_e32 v1, v1, v1
	s_nop 0
	v_add_f32_e32 v0, v0, v1
	v_mov_b32_e32 v1, v14
	s_nop 0
	v_sub_f32_e32 v1, v1, v4
	s_nop 0
	v_mul_f32_e32 v1, v1, v1
	s_nop 0
	v_add_f32_e32 v0, v0, v1
	v_mov_b32_e32 v1, v10
	s_nop 0
	v_sub_f32_e32 v1, v1, v4
	s_nop 0
	v_mul_f32_e32 v1, v1, v1
	s_nop 0
	v_add_f32_e32 v0, v0, v1
	v_mov_b32_e32 v1, v6
	s_nop 0
	v_sub_f32_e32 v1, v1, v4
	s_nop 0
	v_mul_f32_e32 v1, v1, v1
	s_nop 0
	v_add_f32_e32 v0, v0, v1
	v_mov_b32_e32 v1, v2
	s_nop 0
	v_sub_f32_e32 v1, v1, v4
	s_nop 0
	v_mul_f32_e32 v1, v1, v1
	s_nop 0
	v_add_f32_e32 v0, v0, v1
	s_nop 1
	v_add_f32_dpp v0, v0, v0 row_ror:8 row_mask:0xf bank_mask:0xf bound_ctrl:1
	s_nop 1
	v_add_f32_dpp v0, v0, v0 row_ror:4 row_mask:0xf bank_mask:0xf bound_ctrl:1
	s_nop 1
	v_add_f32_dpp v0, v0, v0 row_ror:2 row_mask:0xf bank_mask:0xf bound_ctrl:1
	s_nop 1
	v_add_f32_dpp v0, v0, v0 row_ror:1 row_mask:0xf bank_mask:0xf bound_ctrl:1
	s_nop 0
	v_fmamk_f32 v0, v0, 0x3c000000, v165
	s_nop 0
	v_cmp_gt_f32_e32 vcc, s84, v0
	v_mul_f32_e32 v1, 0x4b800000, v0
	s_nop 0
	v_cndmask_b32_e32 v0, v0, v1, vcc
	v_rsq_f32_e32 v0, v0
	s_nop 0
	v_mul_f32_e32 v1, 0x45800000, v0
	v_cndmask_b32_e32 v5, v0, v1, vcc
	global_load_ushort v200, v[8:9], off offset:3072
	global_load_ushort v201, v[8:9], off offset:3104
	global_load_ushort v202, v[8:9], off offset:3136
	global_load_ushort v203, v[8:9], off offset:3168
	global_load_ushort v204, v[8:9], off offset:3200
	global_load_ushort v205, v[8:9], off offset:3232
	global_load_ushort v206, v[8:9], off offset:3264
	global_load_ushort v207, v[8:9], off offset:3296
	v_lshlrev_b32_e32 v216, 2, v90
	global_load_dword v208, v216, s[0:1]
	global_load_dword v209, v216, s[0:1] offset:64
	global_load_dword v210, v216, s[0:1] offset:128
	global_load_dword v211, v216, s[0:1] offset:192
	global_load_dword v212, v216, s[0:1] offset:256
	global_load_dword v213, v216, s[0:1] offset:320
	global_load_dword v214, v216, s[0:1] offset:384
	global_load_dword v215, v216, s[0:1] offset:448
	v_or_b32_e32 v0, 0x2000, v32
	v_mov_b32_e32 v1, v33
	v_lshl_add_u64 v[0:1], s[78:79], 0, v[0:1]
	v_lshl_add_u64 v[0:1], v[0:1], 0, s[18:19]
	v_lshl_add_u64 v[0:1], v[0:1], 0, v[128:129]
	v_or_b32_e32 v32, 0x3000, v32
	s_waitcnt vmcnt(0)
	v_lshlrev_b32_e32 v16, 16, v200
	v_mov_b32_e32 v17, v208
	v_mul_f32_e32 v41, 0xbfb8aa3b, v16
	v_exp_f32_e32 v41, v41
	s_waitcnt vmcnt(0)
	v_lshlrev_b32_e32 v20, 16, v201
	v_mov_b32_e32 v21, v209
	v_add_f32_e32 v41, 1.0, v41
	v_div_scale_f32 v42, s[6:7], v41, v41, v16
	v_rcp_f32_e32 v43, v42
	s_waitcnt vmcnt(0)
	v_lshlrev_b32_e32 v24, 16, v202
	v_mov_b32_e32 v25, v210
	v_fma_f32 v44, -v42, v43, 1.0
	v_fmac_f32_e32 v43, v44, v43
	v_div_scale_f32 v44, vcc, v16, v41, v16
	v_mul_f32_e32 v45, v44, v43
	v_fma_f32 v46, -v42, v45, v44
	v_fmac_f32_e32 v45, v46, v43
	v_fma_f32 v42, -v42, v45, v44
	v_div_fmas_f32 v42, v42, v43, v45
	v_div_fixup_f32 v16, v42, v41, v16
	s_waitcnt vmcnt(0)
	v_lshlrev_b32_e32 v28, 16, v203
	v_mov_b32_e32 v29, v211
	s_waitcnt vmcnt(0)
	v_lshlrev_b32_e32 v36, 16, v204
	v_mov_b32_e32 v37, v212
	s_waitcnt vmcnt(0)
	v_lshlrev_b32_e32 v38, 16, v205
	v_mov_b32_e32 v39, v213
	s_waitcnt vmcnt(0)
	v_lshlrev_b32_e32 v13, 16, v206
	v_mov_b32_e32 v12, v214
	s_nop 0
	s_waitcnt vmcnt(0)
; DEV float opq(float x) { asm volatile("" : "+v"(x)); return x; }
; DEV void ret_out_item(const Params& p, int l, int item, unsigned char* smem) {
;     ...
; #pragma unroll
;       for (int nt = 0; nt < 8; ++nt) {
;         const float g = gv[nt];
;         const float silu = opq(__fdividef(g, 1.0f + __expf(-g)));
;         const float xn = opq(opq(opq(o[mt][nt][j]) - mu) * rstd);
;         op[nt * 16 + fr] = f2bf(opq(xn * wv[nt]) * silu);
;       }
	v_lshlrev_b32_e32 v9, 16, v207
	v_mov_b32_e32 v8, v215
	s_nop 0
	v_sub_f32_e32 v30, v30, v4
	s_nop 0
	v_mul_f32_e32 v30, v5, v30
	s_nop 0
	v_mul_f32_e32 v17, v17, v30
	s_nop 0
	v_mul_f32_e32 v16, v16, v17
	v_cvt_pk_bf16_f32 v16, v16, s0
	global_store_short v[0:1], v16, off
	v_mul_f32_e32 v16, 0xbfb8aa3b, v20
	v_exp_f32_e32 v16, v16
	s_nop 0
	v_add_f32_e32 v16, 1.0, v16
	v_div_scale_f32 v17, s[6:7], v16, v16, v20
	v_rcp_f32_e32 v30, v17
	s_nop 0
	v_fma_f32 v41, -v17, v30, 1.0
	v_fmac_f32_e32 v30, v41, v30
	v_div_scale_f32 v41, vcc, v20, v16, v20
	v_mul_f32_e32 v42, v41, v30
	v_fma_f32 v43, -v17, v42, v41
	v_fmac_f32_e32 v42, v43, v30
	v_fma_f32 v17, -v17, v42, v41
	v_div_fmas_f32 v17, v17, v30, v42
	v_div_fixup_f32 v16, v17, v16, v20
	s_nop 0
	v_sub_f32_e32 v17, v26, v4
	s_nop 0
	v_mul_f32_e32 v17, v5, v17
	s_nop 0
	v_mul_f32_e32 v17, v21, v17
	s_nop 0
	v_mul_f32_e32 v16, v16, v17
	v_cvt_pk_bf16_f32 v16, v16, s0
	global_store_short v[0:1], v16, off offset:32
	v_mul_f32_e32 v16, 0xbfb8aa3b, v24
	v_exp_f32_e32 v16, v16
	s_nop 0
	v_add_f32_e32 v16, 1.0, v16
	v_div_scale_f32 v17, s[6:7], v16, v16, v24
	v_rcp_f32_e32 v20, v17
	s_nop 0
	v_fma_f32 v21, -v17, v20, 1.0
	v_fmac_f32_e32 v20, v21, v20
	v_div_scale_f32 v21, vcc, v24, v16, v24
	v_mul_f32_e32 v26, v21, v20
	v_fma_f32 v30, -v17, v26, v21
	v_fmac_f32_e32 v26, v30, v20
	v_fma_f32 v17, -v17, v26, v21
	v_div_fmas_f32 v17, v17, v20, v26
	v_div_fixup_f32 v16, v17, v16, v24
	s_nop 0
	v_sub_f32_e32 v17, v22, v4
	s_nop 0
	v_mul_f32_e32 v17, v5, v17
	s_nop 0
	v_mul_f32_e32 v17, v25, v17
	s_nop 0
	v_mul_f32_e32 v16, v16, v17
	v_cvt_pk_bf16_f32 v16, v16, s0
	global_store_short v[0:1], v16, off offset:64
	v_mul_f32_e32 v16, 0xbfb8aa3b, v28
	v_exp_f32_e32 v16, v16
	s_nop 0
	v_add_f32_e32 v16, 1.0, v16
	v_div_scale_f32 v17, s[6:7], v16, v16, v28
	v_rcp_f32_e32 v20, v17
	s_nop 0
	v_fma_f32 v21, -v17, v20, 1.0
	v_fmac_f32_e32 v20, v21, v20
	v_div_scale_f32 v21, vcc, v28, v16, v28
	v_mul_f32_e32 v22, v21, v20
	v_fma_f32 v24, -v17, v22, v21
	v_fmac_f32_e32 v22, v24, v20
	v_fma_f32 v17, -v17, v22, v21
	v_div_fmas_f32 v17, v17, v20, v22
	v_div_fixup_f32 v16, v17, v16, v28
	s_nop 0
	v_sub_f32_e32 v17, v18, v4
	s_nop 0
	v_mul_f32_e32 v17, v5, v17
	s_nop 0
	v_mul_f32_e32 v17, v29, v17
	s_nop 0
	v_mul_f32_e32 v16, v16, v17
	v_cvt_pk_bf16_f32 v16, v16, s0
	global_store_short v[0:1], v16, off offset:96
	v_mul_f32_e32 v16, 0xbfb8aa3b, v36
	v_exp_f32_e32 v16, v16
	s_nop 0
	v_add_f32_e32 v16, 1.0, v16
	v_div_scale_f32 v17, s[6:7], v16, v16, v36
	v_rcp_f32_e32 v18, v17
	s_nop 0
	v_fma_f32 v20, -v17, v18, 1.0
	v_fmac_f32_e32 v18, v20, v18
	v_div_scale_f32 v20, vcc, v36, v16, v36
	v_mul_f32_e32 v21, v20, v18
	v_fma_f32 v22, -v17, v21, v20
	v_fmac_f32_e32 v21, v22, v18
	v_fma_f32 v17, -v17, v21, v20
	v_div_fmas_f32 v17, v17, v18, v21
	v_div_fixup_f32 v16, v17, v16, v36
	s_nop 0
	v_sub_f32_e32 v14, v14, v4
	s_nop 0
	v_mul_f32_e32 v14, v5, v14
	s_nop 0
	v_mul_f32_e32 v14, v37, v14
	s_nop 0
	v_mul_f32_e32 v14, v16, v14
	v_cvt_pk_bf16_f32 v14, v14, s0
	global_store_short v[0:1], v14, off offset:128
	v_mul_f32_e32 v14, 0xbfb8aa3b, v38
	v_exp_f32_e32 v14, v14
	s_nop 0
	v_add_f32_e32 v14, 1.0, v14
	v_div_scale_f32 v16, s[6:7], v14, v14, v38
	v_rcp_f32_e32 v17, v16
	s_nop 0
	v_fma_f32 v18, -v16, v17, 1.0
	v_fmac_f32_e32 v17, v18, v17
	v_div_scale_f32 v18, vcc, v38, v14, v38
	v_mul_f32_e32 v20, v18, v17
	v_fma_f32 v21, -v16, v20, v18
	v_fmac_f32_e32 v20, v21, v17
	v_fma_f32 v16, -v16, v20, v18
	v_div_fmas_f32 v16, v16, v17, v20
	v_div_fixup_f32 v14, v16, v14, v38
	s_nop 0
	v_sub_f32_e32 v10, v10, v4
	s_nop 0
	v_mul_f32_e32 v10, v5, v10
	s_nop 0
	v_mul_f32_e32 v10, v39, v10
	s_nop 0
	v_mul_f32_e32 v10, v14, v10
	v_cvt_pk_bf16_f32 v10, v10, s0
	global_store_short v[0:1], v10, off offset:160
	v_mul_f32_e32 v10, 0xbfb8aa3b, v13
	v_exp_f32_e32 v10, v10
	s_nop 0
	v_add_f32_e32 v10, 1.0, v10
	v_div_scale_f32 v14, s[6:7], v10, v10, v13
	v_rcp_f32_e32 v16, v14
	s_nop 0
	v_fma_f32 v17, -v14, v16, 1.0
	v_fmac_f32_e32 v16, v17, v16
	v_div_scale_f32 v17, vcc, v13, v10, v13
	v_mul_f32_e32 v18, v17, v16
	v_fma_f32 v20, -v14, v18, v17
	v_fmac_f32_e32 v18, v20, v16
	v_fma_f32 v14, -v14, v18, v17
	v_div_fmas_f32 v14, v14, v16, v18
	v_div_fixup_f32 v10, v14, v10, v13
	s_nop 0
	v_sub_f32_e32 v6, v6, v4
	s_nop 0
	v_mul_f32_e32 v6, v5, v6
	s_nop 0
	v_mul_f32_e32 v6, v12, v6
	s_nop 0
	v_mul_f32_e32 v6, v10, v6
	v_cvt_pk_bf16_f32 v6, v6, s0
	global_store_short v[0:1], v6, off offset:192
	v_mul_f32_e32 v6, 0xbfb8aa3b, v9
	v_exp_f32_e32 v6, v6
	s_nop 0
	v_add_f32_e32 v6, 1.0, v6
	v_div_scale_f32 v10, s[6:7], v6, v6, v9
	v_rcp_f32_e32 v12, v10
	s_mov_b64 s[6:7], 0x5000
	v_fma_f32 v13, -v10, v12, 1.0
	v_fmac_f32_e32 v12, v13, v12
	v_div_scale_f32 v13, vcc, v9, v6, v9
	v_mul_f32_e32 v14, v13, v12
	v_fma_f32 v16, -v10, v14, v13
	v_fmac_f32_e32 v14, v16, v12
	v_fma_f32 v10, -v10, v14, v13
	v_div_fmas_f32 v10, v10, v12, v14
	v_div_fixup_f32 v6, v10, v6, v9
	v_lshl_add_u64 v[12:13], v[34:35], 0, s[6:7]
	v_sub_f32_e32 v2, v2, v4
	s_nop 0
	v_mul_f32_e32 v2, v5, v2
	s_waitcnt vmcnt(7)
; DEV float bf2f(u16 h) { return __uint_as_float(((uint32_t)h) << 16); }
; DEV float opq(float x) { asm volatile("" : "+v"(x)); return x; }
; DEV void ret_out_item(const Params& p, int l, int item, unsigned char* smem) {
;     ...
;       float sm = 0.f;
; #pragma unroll
;       for (int nt = 0; nt < 8; ++nt) sm = opq(sm + opq(o[mt][nt][j]));
;       sm = grp16_sum(sm);
;       const float mu = opq(sm * (1.0f / 128.0f));
;       float vs = 0.f;
; #pragma unroll
;       for (int nt = 0; nt < 8; ++nt) { const float d = opq(opq(o[mt][nt][j]) - mu); vs = opq(vs + opq(d * d)); }
;       vs = grp16_sum(vs);
;       const float rstd = opq(rsqrtf(opq(vs * (1.0f / 128.0f) + 1e-5f)));
;       const size_t tok = tok0 + mt * 16 + fq * 4 + j;
;       const u16* __restrict__ gp = p.proj + tok * DIN + C_RG + h * 128;
;       u16* __restrict__ op = p.mix + tok * DM + h * 128;
;       float gv[8], wv[8];
; #pragma unroll
;       for (int nt = 0; nt < 8; ++nt) { gv[nt] = bf2f(gp[nt * 16 + fr]); wv[nt] = gw[nt * 16 + fr]; }
	v_mul_f32_e32 v2, v8, v2
	s_nop 0
	v_mul_f32_e32 v2, v6, v2
	v_cvt_pk_bf16_f32 v2, v2, s0
	global_store_short v[0:1], v2, off offset:224
	v_mov_b32_e32 v0, v31
	v_mov_b32_e32 v1, v27
	v_add_f32_e32 v0, 0, v0
	s_nop 0
	v_add_f32_e32 v0, v0, v1
	v_mov_b32_e32 v1, v23
	s_nop 0
	v_add_f32_e32 v0, v0, v1
	v_mov_b32_e32 v1, v19
	s_nop 0
	v_add_f32_e32 v0, v0, v1
	v_mov_b32_e32 v1, v15
	s_nop 0
	v_add_f32_e32 v0, v0, v1
	v_mov_b32_e32 v1, v11
	s_nop 0
	v_add_f32_e32 v0, v0, v1
	v_mov_b32_e32 v1, v7
	s_nop 0
	v_add_f32_e32 v0, v0, v1
	v_mov_b32_e32 v1, v3
	s_nop 0
	v_add_f32_e32 v0, v0, v1
	v_mov_b32_e32 v1, v27
	s_nop 0
	v_add_f32_dpp v0, v0, v0 row_ror:8 row_mask:0xf bank_mask:0xf bound_ctrl:1
	s_nop 1
	v_add_f32_dpp v0, v0, v0 row_ror:4 row_mask:0xf bank_mask:0xf bound_ctrl:1
	s_nop 1
	v_add_f32_dpp v0, v0, v0 row_ror:2 row_mask:0xf bank_mask:0xf bound_ctrl:1
	s_nop 1
	v_add_f32_dpp v0, v0, v0 row_ror:1 row_mask:0xf bank_mask:0xf bound_ctrl:1
	s_nop 0
	v_mul_f32_e32 v2, 0x3c000000, v0
	v_mov_b32_e32 v0, v31
	s_nop 0
	v_sub_f32_e32 v0, v0, v2
	s_nop 0
	v_mul_f32_e32 v0, v0, v0
	s_nop 0
	v_add_f32_e32 v0, 0, v0
	s_nop 0
	v_sub_f32_e32 v1, v1, v2
	s_nop 0
	v_mul_f32_e32 v1, v1, v1
	s_nop 0
	v_add_f32_e32 v0, v0, v1
	v_mov_b32_e32 v1, v23
	s_nop 0
	v_sub_f32_e32 v1, v1, v2
	s_nop 0
	v_mul_f32_e32 v1, v1, v1
	s_nop 0
	v_add_f32_e32 v0, v0, v1
	v_mov_b32_e32 v1, v19
	s_nop 0
	v_sub_f32_e32 v1, v1, v2
	s_nop 0
	v_mul_f32_e32 v1, v1, v1
	s_nop 0
	v_add_f32_e32 v0, v0, v1
	v_mov_b32_e32 v1, v15
	s_nop 0
	v_sub_f32_e32 v1, v1, v2
	s_nop 0
	v_mul_f32_e32 v1, v1, v1
	s_nop 0
	v_add_f32_e32 v0, v0, v1
	v_mov_b32_e32 v1, v11
	s_nop 0
	v_sub_f32_e32 v1, v1, v2
	s_nop 0
	v_mul_f32_e32 v1, v1, v1
	s_nop 0
	v_add_f32_e32 v0, v0, v1
	v_mov_b32_e32 v1, v7
	s_nop 0
	v_sub_f32_e32 v1, v1, v2
	s_nop 0
	v_mul_f32_e32 v1, v1, v1
	s_nop 0
	v_add_f32_e32 v0, v0, v1
	v_mov_b32_e32 v1, v3
	s_nop 0
	v_sub_f32_e32 v1, v1, v2
	s_nop 0
	v_mul_f32_e32 v1, v1, v1
	s_nop 0
	v_add_f32_e32 v0, v0, v1
	s_nop 1
	v_add_f32_dpp v0, v0, v0 row_ror:8 row_mask:0xf bank_mask:0xf bound_ctrl:1
	s_nop 1
	v_add_f32_dpp v0, v0, v0 row_ror:4 row_mask:0xf bank_mask:0xf bound_ctrl:1
	s_nop 1
	v_add_f32_dpp v0, v0, v0 row_ror:2 row_mask:0xf bank_mask:0xf bound_ctrl:1
	s_nop 1
	v_add_f32_dpp v0, v0, v0 row_ror:1 row_mask:0xf bank_mask:0xf bound_ctrl:1
	s_nop 0
	v_fmamk_f32 v0, v0, 0x3c000000, v165
	s_nop 0
	v_cmp_gt_f32_e32 vcc, s84, v0
	v_mul_f32_e32 v1, 0x4b800000, v0
	s_nop 0
	v_cndmask_b32_e32 v0, v0, v1, vcc
	v_rsq_f32_e32 v0, v0
	s_nop 0
	v_mul_f32_e32 v1, 0x45800000, v0
	v_cndmask_b32_e32 v4, v0, v1, vcc
	global_load_ushort v200, v[12:13], off offset:3072
	global_load_ushort v201, v[12:13], off offset:3104
	global_load_ushort v202, v[12:13], off offset:3136
	global_load_ushort v203, v[12:13], off offset:3168
	global_load_ushort v204, v[12:13], off offset:3200
	global_load_ushort v205, v[12:13], off offset:3232
	global_load_ushort v206, v[12:13], off offset:3264
	global_load_ushort v207, v[12:13], off offset:3296
	v_lshlrev_b32_e32 v216, 2, v90
	global_load_dword v208, v216, s[0:1]
	global_load_dword v209, v216, s[0:1] offset:64
	global_load_dword v210, v216, s[0:1] offset:128
	global_load_dword v211, v216, s[0:1] offset:192
	global_load_dword v212, v216, s[0:1] offset:256
	global_load_dword v213, v216, s[0:1] offset:320
	global_load_dword v214, v216, s[0:1] offset:384
	global_load_dword v215, v216, s[0:1] offset:448
	v_lshl_add_u64 v[0:1], s[78:79], 0, v[32:33]
	v_lshl_add_u64 v[0:1], v[0:1], 0, s[18:19]
	v_lshl_add_u64 v[0:1], v[0:1], 0, v[128:129]
	s_waitcnt vmcnt(0)
	v_lshlrev_b32_e32 v10, 16, v200
	v_mov_b32_e32 v14, v208
	s_waitcnt vmcnt(0)
	v_lshlrev_b32_e32 v16, 16, v201
	v_mov_b32_e32 v17, v209
	s_waitcnt vmcnt(0)
	v_lshlrev_b32_e32 v18, 16, v202
	v_mov_b32_e32 v20, v210
	s_waitcnt vmcnt(0)
	v_lshlrev_b32_e32 v21, 16, v203
	v_mov_b32_e32 v22, v211
	s_waitcnt vmcnt(0)
	v_lshlrev_b32_e32 v24, 16, v204
	v_mov_b32_e32 v25, v212
	s_waitcnt vmcnt(0)
	v_lshlrev_b32_e32 v26, 16, v205
	v_mov_b32_e32 v28, v213
	s_waitcnt vmcnt(0)
	v_lshlrev_b32_e32 v9, 16, v206
	v_mov_b32_e32 v8, v214
	v_mul_f32_e32 v12, 0xbfb8aa3b, v10
	v_exp_f32_e32 v12, v12
	s_waitcnt vmcnt(0)
; DEV float opq(float x) { asm volatile("" : "+v"(x)); return x; }
; DEV void ret_out_item(const Params& p, int l, int item, unsigned char* smem) {
;     ...
; #pragma unroll
;       for (int nt = 0; nt < 8; ++nt) {
;         const float g = gv[nt];
;         const float silu = opq(__fdividef(g, 1.0f + __expf(-g)));
;         const float xn = opq(opq(opq(o[mt][nt][j]) - mu) * rstd);
;         op[nt * 16 + fr] = f2bf(opq(xn * wv[nt]) * silu);
;       }
	v_lshlrev_b32_e32 v6, 16, v207
	v_add_f32_e32 v12, 1.0, v12
	v_mov_b32_e32 v5, v215
	v_div_scale_f32 v13, s[0:1], v12, v12, v10
	v_rcp_f32_e32 v29, v13
	s_nop 0
	v_fma_f32 v30, -v13, v29, 1.0
	v_fmac_f32_e32 v29, v30, v29
	v_div_scale_f32 v30, vcc, v10, v12, v10
	v_mul_f32_e32 v32, v30, v29
	v_fma_f32 v33, -v13, v32, v30
	v_fmac_f32_e32 v32, v33, v29
	v_fma_f32 v13, -v13, v32, v30
	v_div_fmas_f32 v13, v13, v29, v32
	v_div_fixup_f32 v10, v13, v12, v10
	s_nop 0
	v_sub_f32_e32 v12, v31, v2
	s_nop 0
	v_mul_f32_e32 v12, v4, v12
	s_nop 0
	v_mul_f32_e32 v12, v14, v12
	s_nop 0
	v_mul_f32_e32 v10, v10, v12
	v_cvt_pk_bf16_f32 v10, v10, s0
	global_store_short v[0:1], v10, off
	v_mul_f32_e32 v10, 0xbfb8aa3b, v16
	v_exp_f32_e32 v10, v10
	s_nop 0
	v_add_f32_e32 v10, 1.0, v10
	v_div_scale_f32 v12, s[0:1], v10, v10, v16
	v_rcp_f32_e32 v13, v12
	s_nop 0
	v_fma_f32 v14, -v12, v13, 1.0
	v_fmac_f32_e32 v13, v14, v13
	v_div_scale_f32 v14, vcc, v16, v10, v16
	v_mul_f32_e32 v29, v14, v13
	v_fma_f32 v30, -v12, v29, v14
	v_fmac_f32_e32 v29, v30, v13
	v_fma_f32 v12, -v12, v29, v14
	v_div_fmas_f32 v12, v12, v13, v29
	v_div_fixup_f32 v10, v12, v10, v16
	s_nop 0
	v_sub_f32_e32 v12, v27, v2
	s_nop 0
	v_mul_f32_e32 v12, v4, v12
	s_nop 0
	v_mul_f32_e32 v12, v17, v12
	s_nop 0
	v_mul_f32_e32 v10, v10, v12
	v_cvt_pk_bf16_f32 v10, v10, s0
	global_store_short v[0:1], v10, off offset:32
	v_mul_f32_e32 v10, 0xbfb8aa3b, v18
	v_exp_f32_e32 v10, v10
	s_nop 0
	v_add_f32_e32 v10, 1.0, v10
	v_div_scale_f32 v12, s[0:1], v10, v10, v18
	v_rcp_f32_e32 v13, v12
	s_nop 0
	v_fma_f32 v14, -v12, v13, 1.0
	v_fmac_f32_e32 v13, v14, v13
	v_div_scale_f32 v14, vcc, v18, v10, v18
	v_mul_f32_e32 v16, v14, v13
	v_fma_f32 v17, -v12, v16, v14
	v_fmac_f32_e32 v16, v17, v13
	v_fma_f32 v12, -v12, v16, v14
	v_div_fmas_f32 v12, v12, v13, v16
	v_div_fixup_f32 v10, v12, v10, v18
	s_nop 0
	v_sub_f32_e32 v12, v23, v2
	s_nop 0
	v_mul_f32_e32 v12, v4, v12
	s_nop 0
	v_mul_f32_e32 v12, v20, v12
	s_nop 0
	v_mul_f32_e32 v10, v10, v12
	v_cvt_pk_bf16_f32 v10, v10, s0
	global_store_short v[0:1], v10, off offset:64
	v_mul_f32_e32 v10, 0xbfb8aa3b, v21
	v_exp_f32_e32 v10, v10
	s_nop 0
	v_add_f32_e32 v10, 1.0, v10
	v_div_scale_f32 v12, s[0:1], v10, v10, v21
	v_rcp_f32_e32 v13, v12
	s_nop 0
	v_fma_f32 v14, -v12, v13, 1.0
	v_fmac_f32_e32 v13, v14, v13
	v_div_scale_f32 v14, vcc, v21, v10, v21
	v_mul_f32_e32 v16, v14, v13
	v_fma_f32 v17, -v12, v16, v14
	v_fmac_f32_e32 v16, v17, v13
	v_fma_f32 v12, -v12, v16, v14
	v_div_fmas_f32 v12, v12, v13, v16
	v_div_fixup_f32 v10, v12, v10, v21
	s_nop 0
	v_sub_f32_e32 v12, v19, v2
	s_nop 0
	v_mul_f32_e32 v12, v4, v12
	s_nop 0
	v_mul_f32_e32 v12, v22, v12
	s_nop 0
	v_mul_f32_e32 v10, v10, v12
	v_cvt_pk_bf16_f32 v10, v10, s0
	global_store_short v[0:1], v10, off offset:96
	v_mul_f32_e32 v10, 0xbfb8aa3b, v24
	v_exp_f32_e32 v10, v10
	s_nop 0
	v_add_f32_e32 v10, 1.0, v10
	v_div_scale_f32 v12, s[0:1], v10, v10, v24
	v_rcp_f32_e32 v13, v12
	s_nop 0
	v_fma_f32 v14, -v12, v13, 1.0
	v_fmac_f32_e32 v13, v14, v13
	v_div_scale_f32 v14, vcc, v24, v10, v24
	v_mul_f32_e32 v16, v14, v13
	v_fma_f32 v17, -v12, v16, v14
	v_fmac_f32_e32 v16, v17, v13
	v_fma_f32 v12, -v12, v16, v14
	v_div_fmas_f32 v12, v12, v13, v16
	v_div_fixup_f32 v10, v12, v10, v24
	s_nop 0
	v_sub_f32_e32 v12, v15, v2
	s_nop 0
	v_mul_f32_e32 v12, v4, v12
	s_nop 0
	v_mul_f32_e32 v12, v25, v12
	s_nop 0
	v_mul_f32_e32 v10, v10, v12
	v_cvt_pk_bf16_f32 v10, v10, s0
	global_store_short v[0:1], v10, off offset:128
	v_mul_f32_e32 v10, 0xbfb8aa3b, v26
	v_exp_f32_e32 v10, v10
	s_nop 0
	v_add_f32_e32 v10, 1.0, v10
	v_div_scale_f32 v12, s[0:1], v10, v10, v26
	v_rcp_f32_e32 v13, v12
	s_nop 0
	v_fma_f32 v14, -v12, v13, 1.0
	v_fmac_f32_e32 v13, v14, v13
	v_div_scale_f32 v14, vcc, v26, v10, v26
	v_mul_f32_e32 v15, v14, v13
	v_fma_f32 v16, -v12, v15, v14
	v_fmac_f32_e32 v15, v16, v13
	v_fma_f32 v12, -v12, v15, v14
	v_div_fmas_f32 v12, v12, v13, v15
	v_div_fixup_f32 v10, v12, v10, v26
	s_nop 0
	v_sub_f32_e32 v11, v11, v2
	s_nop 0
	v_mul_f32_e32 v11, v4, v11
	s_nop 0
	v_mul_f32_e32 v11, v28, v11
	s_nop 0
	v_mul_f32_e32 v10, v10, v11
	v_cvt_pk_bf16_f32 v10, v10, s0
	global_store_short v[0:1], v10, off offset:160
	v_mul_f32_e32 v10, 0xbfb8aa3b, v9
	v_exp_f32_e32 v10, v10
	s_nop 0
	v_add_f32_e32 v10, 1.0, v10
	v_div_scale_f32 v11, s[0:1], v10, v10, v9
	v_rcp_f32_e32 v12, v11
	s_nop 0
	v_fma_f32 v13, -v11, v12, 1.0
	v_fmac_f32_e32 v12, v13, v12
	v_div_scale_f32 v13, vcc, v9, v10, v9
	v_mul_f32_e32 v14, v13, v12
	v_fma_f32 v15, -v11, v14, v13
	v_fmac_f32_e32 v14, v15, v12
	v_fma_f32 v11, -v11, v14, v13
	v_div_fmas_f32 v11, v11, v12, v14
	v_div_fixup_f32 v9, v11, v10, v9
	s_nop 0
	v_sub_f32_e32 v7, v7, v2
	s_nop 0
	v_mul_f32_e32 v7, v4, v7
	s_nop 0
	v_mul_f32_e32 v7, v8, v7
	s_nop 0
	v_mul_f32_e32 v7, v9, v7
	v_cvt_pk_bf16_f32 v7, v7, s0
	global_store_short v[0:1], v7, off offset:192
	v_mul_f32_e32 v7, 0xbfb8aa3b, v6
	v_exp_f32_e32 v7, v7
	s_nop 0
	v_add_f32_e32 v7, 1.0, v7
	v_div_scale_f32 v8, s[0:1], v7, v7, v6
	v_rcp_f32_e32 v9, v8
	s_nop 0
	v_fma_f32 v10, -v8, v9, 1.0
	v_fmac_f32_e32 v9, v10, v9
	v_div_scale_f32 v10, vcc, v6, v7, v6
	v_mul_f32_e32 v11, v10, v9
	v_fma_f32 v12, -v8, v11, v10
	v_fmac_f32_e32 v11, v12, v9
	v_fma_f32 v8, -v8, v11, v10
	v_div_fmas_f32 v8, v8, v9, v11
	v_div_fixup_f32 v6, v8, v7, v6
	s_nop 0
	v_sub_f32_e32 v2, v3, v2
	s_nop 0
	v_mul_f32_e32 v2, v4, v2
	s_waitcnt vmcnt(7)
	v_mul_f32_e32 v2, v5, v2
	s_nop 0
	v_mul_f32_e32 v2, v6, v2
	v_cvt_pk_bf16_f32 v2, v2, s0
	global_store_short v[0:1], v2, off offset:224
	s_cbranch_scc1 .LBB0_408
